# prep_c: conv taps staged once per half-block; per-token gate inputs and the head's dt_bias/a_log loaded at the top of the chunk instead of inside the wave-0 gate block
# speedup vs baseline: 1.0477x; 1.0376x over previous
; DI void phase_prep_c(int wv_, int vb_, int nvb_, char* ws_, const Ctx& p, char* smem, int half) {
;     ...
;       const int i = tid >> 2, p4 = tid & 3;
; #pragma unroll 1
;       for (int which = 0; which < 3; ++which) {
;         const int colbase = which * 1024 + hd * 128 + p4 * 32;
;         bf16x8 xv[4][4];
; #pragma unroll
;         for (int j = 0; j < 4; ++j) {
;           const int ri = i - 3 + j;
;           const u16* src = PQ + ((size_t)b * 2048 + nc * 64 + (ri >= 0 || nc > 0 ? ri : 0)) * 3072 + colbase;
;           const bool zr = (ri < 0 && nc == 0 && half == 0);
;           if (ri < 0 && nc == 0 && half == 1) src = halo + ((size_t)b * 3 + (3 + ri)) * 3072 + colbase;
; #pragma unroll
;           for (int q = 0; q < 4; ++q) { bf16x8 t_ = *(const bf16x8*)(src + q * 8);
; #pragma unroll
;             for (int e = 0; e < 8; ++e) t_[e] = zr ? (short)0 : t_[e];
;             xv[j][q] = t_; }
;     ...
;     if ((tidx(wv_) >> 6) == 0) {
;       const int lane = tidx(wv_) & 63;
;       const size_t tok = (size_t)b * SEQ + n * 64 + lane;
;       float bb = side[tok * 16 + hd], aa = side[tok * 16 + 8 + hd];
.LBB0_253:
	s_or_b64 exec, exec, s[2:3]
	s_ashr_i32 s14, s12, 8
	s_and_b32 s18, s12, 31
	s_ashr_i32 s15, s14, 31
	s_lshl_b64 s[0:1], s[14:15], 11
	s_lshl_b32 s44, s18, 6
	s_lshl_b64 s[100:101], s[14:15], 12
	v_readlane_b32 vcc_lo, v255, 10
	v_mov_b32_e32 v229, s101
	s_or_b32 s100, s100, s44
	s_or_b32 s100, s100, vcc_lo
	v_or_b32_e32 v228, s100, v204
	v_lshlrev_b64 v[228:229], 6, v[228:229]
	v_lshl_add_u64 v[228:229], s[58:59], 0, v[228:229]
	s_lshl_b32 s100, s13, 2
	s_mov_b32 s101, 0
	v_lshl_add_u64 v[228:229], v[228:229], 0, s[100:101]
	v_mov_b32_e32 v232, s100
	global_load_dword v230, v[228:229], off
	global_load_dword v231, v[228:229], off offset:32
	v_readlane_b32 s100, v254, 26
	v_readlane_b32 s101, v254, 27
	s_nop 4
	global_load_dword v233, v232, s[100:101]
	v_readlane_b32 s100, v254, 24
	v_readlane_b32 s101, v254, 25
	s_nop 4
	global_load_dword v234, v232, s[100:101]
	s_min_i32 s45, s69, 0x7ff
	s_or_b32 s0, s0, s44
	s_cmp_lg_u32 s18, 0
	s_cselect_b64 s[2:3], -1, 0
	s_cmp_eq_u32 s18, 0
	v_ashrrev_i32_e32 v5, 2, v2
	s_cselect_b64 s[62:63], -1, 0
	s_cmp_eq_u32 s18, 31
	v_lshlrev_b32_e32 v0, 5, v4
	s_cselect_b64 s[18:19], -1, 0
	v_cmp_lt_i32_e32 vcc, 60, v5
	s_mul_i32 s64, s14, 3
	v_and_b32_e32 v96, 0x60, v0
	v_add_u32_e32 v8, -3, v5
	s_and_b64 s[18:19], s[18:19], vcc
	s_ashr_i32 s65, s64, 31
	v_subrev_u32_e32 v0, 61, v5
	v_cmp_lt_i32_e32 vcc, 2, v5
	v_lshl_add_u64 v[2:3], v[0:1], 0, s[64:65]
	v_ashrrev_i32_e32 v0, 31, v8
	s_or_b64 vcc, s[2:3], vcc
	v_cndmask_b32_e32 v9, 0, v0, vcc
	v_cndmask_b32_e32 v8, 0, v8, vcc
	v_lshl_add_u64 v[8:9], s[0:1], 0, v[8:9]
	v_mov_b64_e32 v[10:11], s[86:87]
	v_mad_u64_u32 v[12:13], s[72:73], v8, s36, v[10:11]
	v_cmp_gt_i32_e32 vcc, 3, v5
	v_mad_i32_i24 v0, v9, s36, v13
	s_and_b64 s[90:91], s[62:63], vcc
	v_add_u32_e32 v13, -2, v5
	v_cmp_lt_i32_e32 vcc, 1, v5
	s_waitcnt lgkmcnt(0)
	v_ashrrev_i32_e32 v16, 31, v13
	s_or_b64 vcc, s[2:3], vcc
	v_mad_u64_u32 v[6:7], s[72:73], v2, s36, 0
	v_cndmask_b32_e32 v17, 0, v16, vcc
	v_cndmask_b32_e32 v16, 0, v13, vcc
	v_mad_i32_i24 v3, v3, s36, v7
	v_add_u32_e32 v7, s64, v5
	v_mov_b64_e32 v[8:9], s[6:7]
	v_lshl_add_u64 v[16:17], s[0:1], 0, v[16:17]
	v_mad_i64_i32 v[14:15], s[64:65], v7, s36, v[8:9]
	v_mad_u64_u32 v[18:19], s[64:65], v16, s36, v[10:11]
	v_cmp_gt_i32_e32 vcc, 2, v5
	v_add_u32_e32 v13, 1, v7
	v_mad_i32_i24 v19, v17, s36, v19
	s_and_b64 s[64:65], s[62:63], vcc
	v_mad_i64_i32 v[16:17], s[76:77], v13, s36, v[8:9]
	v_add_u32_e32 v13, -1, v5
	v_cmp_lt_i32_e32 vcc, 0, v5
	v_ashrrev_i32_e32 v20, 31, v13
	s_or_b64 vcc, s[2:3], vcc
	v_cndmask_b32_e32 v21, 0, v20, vcc
	v_cndmask_b32_e32 v20, 0, v13, vcc
	v_cmp_gt_i32_e32 vcc, 1, v5
	s_and_b64 s[96:97], s[62:63], vcc
	v_cmp_lt_i32_e32 vcc, -1, v5
	v_ashrrev_i32_e32 v2, 31, v5
	s_or_b64 vcc, s[2:3], vcc
	v_cndmask_b32_e32 v25, 0, v2, vcc
	v_cndmask_b32_e32 v24, 0, v5, vcc
	v_lshl_add_u64 v[20:21], s[0:1], 0, v[20:21]
	v_lshl_add_u64 v[24:25], s[0:1], 0, v[24:25]
	v_mad_u64_u32 v[22:23], s[76:77], v20, s36, v[10:11]
	v_mad_u64_u32 v[10:11], s[0:1], v24, s36, v[10:11]
	v_cmp_gt_i32_e32 vcc, 0, v5
	v_add_u32_e32 v13, 2, v7
	s_and_b64 s[0:1], s[62:63], vcc
	s_and_b64 vcc, s[10:11], s[90:91]
	v_mad_i32_i24 v23, v21, s36, v23
	v_mad_i64_i32 v[20:21], s[94:95], v13, s36, v[8:9]
	v_cndmask_b32_e32 v13, v0, v15, vcc
	v_cndmask_b32_e32 v12, v12, v14, vcc
	s_and_b64 vcc, s[10:11], s[64:65]
	v_cndmask_b32_e32 v15, v19, v17, vcc
	v_cndmask_b32_e32 v14, v18, v16, vcc
	s_and_b64 vcc, s[10:11], s[96:97]
	s_and_b64 s[94:95], s[8:9], s[0:1]
	v_cndmask_b32_e32 v17, v23, v21, vcc
	v_cndmask_b32_e32 v16, v22, v20, vcc
	s_and_b64 vcc, s[10:11], s[0:1]
	s_lshl_b32 s0, s45, 3
	v_add_u32_e32 v7, 3, v7
	v_and_b32_e32 v0, 3, v4
	s_and_b32 s0, s0, 0x700
	v_mad_i32_i24 v2, v25, s36, v11
	v_mad_i64_i32 v[8:9], s[2:3], v7, s36, v[8:9]
	v_lshl_add_u32 v98, v0, 7, v95
	v_lshl_or_b32 v0, v96, 1, s0
	v_cndmask_b32_e32 v9, v2, v9, vcc
	v_cndmask_b32_e32 v8, v10, v8, vcc
	v_or_b32_e32 v2, v6, v0
	s_and_b64 s[18:19], s[8:9], s[18:19]
	s_and_b64 s[88:89], s[8:9], s[90:91]
	s_and_b64 s[72:73], s[8:9], s[64:65]
	s_and_b64 s[76:77], s[8:9], s[96:97]
	v_mul_lo_u32 v97, v5, s84
	v_lshl_add_u64 v[78:79], s[78:79], 0, v[2:3]
	v_lshl_add_u64 v[80:81], v[12:13], 0, v[0:1]
	v_lshl_add_u64 v[82:83], v[14:15], 0, v[0:1]
	v_lshl_add_u64 v[84:85], v[8:9], 0, v[0:1]
	v_lshl_add_u64 v[86:87], v[16:17], 0, v[0:1]
	s_mov_b64 s[96:97], 0
	s_waitcnt vmcnt(63) expcnt(7) lgkmcnt(15)
	s_barrier
	s_branch .LBB0_255

; DI float shup(float v, int d) { const int l = lane_now(); return __int_as_float(__builtin_amdgcn_ds_bpermute((l - d >= 0 ? l - d : l) << 2, __float_as_int(v))); }
; DI void phase_prep_c(int wv_, int vb_, int nvb_, char* ws_, const Ctx& p, char* smem, int half) {
;     ...
;     if ((tidx(wv_) >> 6) == 0) {
;       const int lane = tidx(wv_) & 63;
;       const size_t tok = (size_t)b * SEQ + n * 64 + lane;
;       float bb = side[tok * 16 + hd], aa = side[tok * 16 + 8 + hd];
;       float beta = 1.0f / (1.0f + __expf(-bb));
;       float xx = aa + p.c_dt_bias[hd];
;       float sp = fmaxf(xx, 0.f) + log1pf(__expf(-fabsf(xx)));
;       float gcv = -__expf(p.c_a_log[hd]) * sp;
; #pragma unroll
;       for (int off = 1; off < 64; off <<= 1) { float v = shup(gcv, off); if (lane >= off) gcv += v; }
.LBB0_259:
	s_mov_b32 s0, s33
	v_mov_b32_e32 v0, v204
	s_nop 0
	v_lshl_or_b32 v0, s0, 6, v0
	v_cmp_gt_u32_e32 vcc, 64, v0
	s_and_saveexec_b64 s[2:3], vcc
	s_cbranch_execz .LBB0_262
	s_mov_b32 s0, s33
	v_mov_b32_e32 v0, v204
	s_lshl_b64 s[0:1], s[14:15], 12
	v_readlane_b32 s14, v255, 10
	s_or_b32 s14, s44, s14
	v_and_b32_e32 v0, 63, v0
	s_or_b32 s0, s0, s14
	v_or_b32_e32 v2, s0, v0
	v_mov_b32_e32 v3, s1
	v_lshlrev_b64 v[2:3], 6, v[2:3]
	v_lshl_add_u64 v[2:3], s[58:59], 0, v[2:3]
	s_lshl_b32 s84, s13, 2
	v_lshl_add_u64 v[2:3], v[2:3], 0, s[84:85]
	s_waitcnt vmcnt(0)
	v_mov_b32_e32 v4, v230
	v_mov_b32_e32 v5, v231
	v_readlane_b32 s60, v254, 22
	v_mov_b32_e32 v3, s84
	v_readlane_b32 s64, v254, 26
	v_readlane_b32 s65, v254, 27
	s_mov_b32 s0, 0xbfb8aa3b
	v_readlane_b32 s62, v254, 24
	v_readlane_b32 s63, v254, 25
	s_movk_i32 s84, 0x110
	v_readlane_b32 s61, v254, 23
	v_readlane_b32 s66, v254, 28
	v_readlane_b32 s67, v254, 29
	s_waitcnt vmcnt(1)
	v_mul_f32_e32 v2, 0xbfb8aa3b, v4
	v_mov_b32_e32 v4, v233
	v_exp_f32_e32 v2, v2
	v_mov_b32_e32 v3, v234
	v_add_f32_e32 v2, 1.0, v2
	s_waitcnt vmcnt(1)
	v_add_f32_e32 v4, v5, v4
	v_max_f32_e32 v6, 0, v4
	v_mul_f32_e64 v4, |v4|, s0
	v_exp_f32_e32 v7, v4
	s_mov_b32 s0, 0x3f2aaaab
	s_waitcnt vmcnt(0)
	v_mul_f32_e32 v3, 0x3fb8aa3b, v3
	v_exp_f32_e32 v3, v3
	v_add_f32_e32 v8, 1.0, v7
	v_add_f32_e32 v4, -1.0, v8
	v_sub_f32_e32 v5, v4, v8
	v_add_f32_e32 v5, 1.0, v5
	v_sub_f32_e32 v4, v7, v4
	v_add_f32_e32 v9, v4, v5
	v_frexp_mant_f32_e32 v4, v8
	v_cmp_gt_f32_e32 vcc, s0, v4
	v_cvt_f64_f32_e32 v[4:5], v8
	v_frexp_exp_i32_f64_e32 v4, v[4:5]
	v_subbrev_co_u32_e32 v4, vcc, 0, v4, vcc
	v_sub_u32_e32 v5, 0, v4
	v_ldexp_f32 v8, v8, v5
	v_ldexp_f32 v5, v9, v5
	v_add_f32_e32 v9, -1.0, v8
	v_add_f32_e32 v10, 1.0, v9
	v_sub_f32_e32 v10, v8, v10
	v_add_f32_e32 v10, v5, v10
	v_add_f32_e32 v11, v9, v10
	v_sub_f32_e32 v9, v11, v9
	v_sub_f32_e32 v9, v10, v9
	v_add_f32_e32 v10, 1.0, v8
	v_add_f32_e32 v12, -1.0, v10
	v_sub_f32_e32 v8, v8, v12
	v_add_f32_e32 v5, v5, v8
	v_add_f32_e32 v8, v10, v5
	v_sub_f32_e32 v10, v8, v10
	v_sub_f32_e32 v5, v5, v10
	v_rcp_f32_e32 v10, v8
	v_cvt_f32_i32_e32 v4, v4
	s_mov_b32 s0, 0x3f317218
	v_cmp_neq_f32_e32 vcc, s49, v7
	v_mul_f32_e32 v12, v11, v10
	v_mul_f32_e32 v13, v8, v12
	v_fma_f32 v14, v12, v8, -v13
	v_fmac_f32_e32 v14, v12, v5
	v_add_f32_e32 v15, v13, v14
	v_sub_f32_e32 v16, v11, v15
	v_sub_f32_e32 v11, v11, v16
	v_sub_f32_e32 v13, v15, v13
	v_sub_f32_e32 v11, v11, v15
	v_add_f32_e32 v9, v9, v11
	v_sub_f32_e32 v11, v13, v14
	v_add_f32_e32 v9, v11, v9
	v_add_f32_e32 v11, v16, v9
	v_mul_f32_e32 v13, v10, v11
	v_mul_f32_e32 v14, v8, v13
	v_fma_f32 v8, v13, v8, -v14
	v_fmac_f32_e32 v8, v13, v5
	v_sub_f32_e32 v5, v16, v11
	v_add_f32_e32 v5, v9, v5
	v_add_f32_e32 v9, v14, v8
	v_sub_f32_e32 v15, v11, v9
	v_sub_f32_e32 v11, v11, v15
	v_sub_f32_e32 v14, v9, v14
	v_sub_f32_e32 v9, v11, v9
	v_add_f32_e32 v5, v5, v9
	v_sub_f32_e32 v8, v14, v8
	v_add_f32_e32 v5, v8, v5
	v_add_f32_e32 v8, v12, v13
	v_add_f32_e32 v5, v15, v5
	v_sub_f32_e32 v9, v8, v12
	v_mul_f32_e32 v5, v10, v5
	v_sub_f32_e32 v9, v13, v9
	v_add_f32_e32 v5, v9, v5
	v_mul_f32_e32 v12, 0x3f317218, v4
	v_add_f32_e32 v9, v8, v5
	v_fma_f32 v13, v4, s0, -v12
	v_mul_f32_e32 v10, v9, v9
	v_mov_b32_e32 v11, 0x3ecc95a3
	v_fmac_f32_e32 v13, 0xb102e308, v4
	v_sub_f32_e32 v4, v9, v8
	v_fmamk_f32 v11, v10, 0x3e9b6dac, v11
	v_sub_f32_e32 v4, v5, v4
	v_add_f32_e32 v5, v12, v13
	v_fmaak_f32 v11, v10, v11, 0x3f2aaada
	v_sub_f32_e32 v8, v5, v12
	v_ldexp_f32 v12, v9, 1
	v_mul_f32_e32 v9, v9, v10
	v_mul_f32_e32 v9, v9, v11
	v_add_f32_e32 v10, v12, v9
	v_sub_f32_e32 v11, v10, v12
	v_ldexp_f32 v4, v4, 1
	v_sub_f32_e32 v9, v9, v11
	v_add_f32_e32 v4, v4, v9
	v_add_f32_e32 v9, v10, v4
	v_sub_f32_e32 v10, v9, v10
	v_sub_f32_e32 v4, v4, v10
	v_add_f32_e32 v10, v5, v9
	v_sub_f32_e32 v11, v10, v5
	v_sub_f32_e32 v12, v10, v11
	v_sub_f32_e32 v8, v13, v8
	v_sub_f32_e32 v5, v5, v12
	v_sub_f32_e32 v9, v9, v11
	v_add_f32_e32 v5, v9, v5
	v_add_f32_e32 v9, v8, v4
	v_sub_f32_e32 v11, v9, v8
	v_sub_f32_e32 v12, v9, v11
	v_sub_f32_e32 v8, v8, v12
	v_sub_f32_e32 v4, v4, v11
	v_add_f32_e32 v5, v9, v5
	v_add_f32_e32 v4, v4, v8
	v_add_f32_e32 v8, v10, v5
	v_sub_f32_e32 v9, v8, v10
	v_sub_f32_e32 v5, v5, v9
	v_add_f32_e32 v4, v4, v5
	v_add_f32_e32 v4, v8, v4
	v_mov_b32_e32 v5, 0x7f800000
	v_cndmask_b32_e32 v4, v5, v4, vcc
	v_cmp_ngt_f32_e32 vcc, -1.0, v7
	v_mov_b32_e32 v5, 0x7fc00000
	s_mov_b32 s0, 0x33800000
	v_cndmask_b32_e32 v4, v5, v4, vcc
	v_cmp_neq_f32_e32 vcc, -1.0, v7
	s_nop 1
	v_cndmask_b32_e32 v4, v207, v4, vcc
	v_cmp_lt_f32_e64 vcc, |v7|, s0
	s_nop 1
	v_cndmask_b32_e32 v4, v4, v7, vcc
	v_add_f32_e32 v4, v6, v4
	v_mov_b32_e32 v6, v204
	v_mul_f32_e64 v5, v4, -v3
	v_cmp_lt_i32_e32 vcc, 0, v6
	s_nop 1
	v_subbrev_co_u32_e32 v6, vcc, 0, v6, vcc
	v_lshlrev_b32_e32 v6, 2, v6
	ds_bpermute_b32 v6, v6, v5
	v_cmp_eq_u32_e32 vcc, 0, v0
	s_waitcnt lgkmcnt(0)
; DI float shup(float v, int d) { const int l = lane_now(); return __int_as_float(__builtin_amdgcn_ds_bpermute((l - d >= 0 ? l - d : l) << 2, __float_as_int(v))); }
; DI void phase_prep_c(int wv_, int vb_, int nvb_, char* ws_, const Ctx& p, char* smem, int half) {
;     ...
;       float beta = 1.0f / (1.0f + __expf(-bb));
;       float xx = aa + p.c_dt_bias[hd];
;       float sp = fmaxf(xx, 0.f) + log1pf(__expf(-fabsf(xx)));
;       float gcv = -__expf(p.c_a_log[hd]) * sp;
; #pragma unroll
;       for (int off = 1; off < 64; off <<= 1) { float v = shup(gcv, off); if (lane >= off) gcv += v; }
;       sbeta[lane] = beta; sgc[lane] = gcv; sbg[lane] = beta * __expf(gcv);
;       if (lane == 63) GL[uix] = __expf(gcv);
	v_fma_f32 v3, v4, -v3, v6
	v_mov_b32_e32 v4, v204
	v_cndmask_b32_e32 v3, v3, v5, vcc
	v_cmp_gt_i32_e32 vcc, 2, v4
	v_lshlrev_b32_e32 v4, 2, v4
	v_add_u32_e32 v5, -8, v4
	v_cndmask_b32_e32 v4, v5, v4, vcc
	ds_bpermute_b32 v4, v4, v3
	v_cmp_gt_u32_e32 vcc, 2, v0
	s_waitcnt lgkmcnt(0)
	v_add_f32_e32 v4, v3, v4
	v_cndmask_b32_e32 v3, v4, v3, vcc
	v_mov_b32_e32 v4, v204
	s_nop 0
	v_cmp_gt_i32_e32 vcc, 4, v4
	v_lshlrev_b32_e32 v4, 2, v4
	v_add_u32_e32 v5, -16, v4
	v_cndmask_b32_e32 v4, v5, v4, vcc
	ds_bpermute_b32 v4, v4, v3
	v_cmp_gt_u32_e32 vcc, 4, v0
	s_waitcnt lgkmcnt(0)
	v_add_f32_e32 v4, v3, v4
	v_cndmask_b32_e32 v3, v4, v3, vcc
	v_mov_b32_e32 v4, v204
	s_nop 0
	v_cmp_gt_i32_e32 vcc, 8, v4
	v_lshlrev_b32_e32 v4, 2, v4
	v_subrev_u32_e32 v5, 32, v4
	v_cndmask_b32_e32 v4, v5, v4, vcc
	ds_bpermute_b32 v4, v4, v3
	v_cmp_gt_u32_e32 vcc, 8, v0
	s_waitcnt lgkmcnt(0)
	v_add_f32_e32 v4, v3, v4
	v_cndmask_b32_e32 v3, v4, v3, vcc
	v_mov_b32_e32 v4, v204
	s_nop 0
	v_cmp_gt_i32_e32 vcc, 16, v4
	v_lshlrev_b32_e32 v4, 2, v4
	v_subrev_u32_e32 v5, 64, v4
	v_cndmask_b32_e32 v4, v5, v4, vcc
	ds_bpermute_b32 v4, v4, v3
	v_cmp_gt_u32_e32 vcc, 16, v0
	s_waitcnt lgkmcnt(0)
	v_add_f32_e32 v4, v3, v4
	v_cndmask_b32_e32 v3, v4, v3, vcc
	v_mov_b32_e32 v4, v204
	s_nop 0
	v_cmp_gt_i32_e32 vcc, 32, v4
	v_lshlrev_b32_e32 v4, 2, v4
	v_add_u32_e32 v5, 0xffffff80, v4
	v_cndmask_b32_e32 v4, v5, v4, vcc
	ds_bpermute_b32 v4, v4, v3
	v_cmp_gt_u32_e32 vcc, 32, v0
	s_waitcnt lgkmcnt(0)
	v_add_f32_e32 v4, v3, v4
	v_cndmask_b32_e32 v3, v4, v3, vcc
	v_div_scale_f32 v4, s[0:1], v2, v2, 1.0
	v_rcp_f32_e32 v5, v4
	s_nop 0
	v_fma_f32 v6, -v4, v5, 1.0
	v_fmac_f32_e32 v5, v6, v5
	v_div_scale_f32 v6, vcc, 1.0, v2, 1.0
	v_mul_f32_e32 v7, v6, v5
	v_fma_f32 v8, -v4, v7, v6
	v_fmac_f32_e32 v7, v8, v5
	v_fma_f32 v4, -v4, v7, v6
	v_div_fmas_f32 v4, v4, v5, v7
	v_div_fixup_f32 v4, v4, v2, 1.0
	v_mul_f32_e32 v2, 0x3fb8aa3b, v3
	v_exp_f32_e32 v2, v2
	v_lshl_add_u32 v5, v0, 2, v214
	ds_write2st64_b32 v5, v4, v3 offset0:68 offset1:69
	v_cmp_eq_u32_e32 vcc, 63, v0
	v_mul_f32_e32 v3, v4, v2
	ds_write_b32 v5, v3 offset:17920
	s_and_b64 exec, exec, vcc
	s_cbranch_execz .LBB0_262
	s_ashr_i32 s13, s12, 31
	s_lshl_b64 s[0:1], s[12:13], 2
	v_readlane_b32 s13, v255, 8
	s_add_u32 s0, s13, s0
	v_readlane_b32 s13, v255, 9
	s_addc_u32 s1, s13, s1
	global_store_dword v1, v2, s[0:1]

; #define PG8_LAS __attribute__((address_space(3)))
; __global__ void __launch_bounds__(512, 2) mega(Params pp) {
;     ...
;     switch (op) {
;       case OP_CONVERT: phase_convert(wv_, vb_, nvb_, ws_, p, smem); break;
;       case OP_NORM_MIX: phase_norm(wv_, vb_, nvb_, xcur, p.norm_mix + l * DM, H); break;
;       case OP_GEMM_IN:
;         if (kind == 0) { pg8::EpiB16HN E; E.O = Pm; E.ldc = 4608; E.ncols_norm = 3072; E.nq_cols = 1536; E.gq = p.a_q_gain + j * 64; E.gk = p.a_k_gain + j * 64; E.T = (PG8_LAS float*)(smem0 + 131072);
;           run_gemm(wv8_, H, WT + (size_t)j * 4718592u, 4608, 1024, -1, E); }
;         else if (kind == 1) { pg8::EpiB16HN E; E.O = Pm; E.ldc = 2304; E.ncols_norm = 1280; E.nq_cols = 1024; E.gq = p.b_q_gain; E.gk = p.b_k_gain; E.T = (PG8_LAS float*)(smem0 + 131072);
;           run_gemm(wv8_, H, WT + wOff(4), 2304, 1024, -1, E); }
;         else { pg8::EpiCIn E; E.Q = (u16*)(ws_ + WS_CQKV); E.G = (u16*)(ws_ + WS_CG); E.S = (float*)(ws_ + WS_SIDE); E.half = half;
;           run_gemm(wv8_, H, WT + wOff(6), 4352, 1024, half, E); }
;         break;
;       case OP_HEADNORM:
;         if (kind == 0) phase_headnorm(wv_, vb_, nvb_, Pm, 4608, 48, 24, p.a_q_gain + j * 64, p.a_k_gain + j * 64);
;         else phase_headnorm(wv_, vb_, nvb_, Pm, 2304, 20, 16, p.b_q_gain, p.b_k_gain);
;         break;
;       case OP_ATTN_A: phase_attn_a(wv_, vb_, nvb_, ws_, p, smem); break;
;       case OP_COMBINE_A: phase_combine_a(wv_, vb_, nvb_, ws_, p); break;
;       case OP_GEMM_OUT:
;       case OP_GEMM_W2: {
;         pg8::EpiResid E; E.C = p.out; E.X = xcur;
;         const u16* Ag = H; int Kg = 1024; unsigned wo = wOff(7);
;         if (op == OP_GEMM_W2) { Ag = Pm; Kg = 4096; wo = wOff(12) + (unsigned)l * 4194304u; }
;         else if (kind == 0) { Kg = 512; wo = wOff(2) + (unsigned)j * 524288u; }
;         else if (kind == 1) { wo = wOff(5); }
;         run_gemm(wv8_, Ag, WT + wo, 1024, Kg, -1, E);
;         break; }
;       case OP_MIX_B: if (half == 0) phase_mix_b(wv_, vb_, nvb_, ws_, p, smem); else phase_mix_b2(wv_, vb_, nvb_, ws_, p, smem); break;
;       case OP_PREP_C: phase_prep_c(wv_, vb_, nvb_, ws_, p, smem, half); break;
;       case OP_SCAN_C: phase_scan_c(wv_, vb_, nvb_, ws_, p, smem, half); break;
;       case OP_SCAN_GEMM:
;         if ((int)blockIdx.x < 64) phase_scan_c(wv_, vb_, nvb_, ws_, p, smem, 0);
.LBB0_447:
	s_nop 0
	s_nop 0
	s_nop 0
	s_nop 0
	s_nop 0
	s_nop 0
	s_nop 0
	s_nop 0
	s_nop 0
	s_nop 0
	s_nop 0
	s_nop 0
	s_nop 0
	s_nop 0
	s_nop 0
	s_mov_b64 s[2:3], 0
